# grid barriers: the XCC leader issues its acquire invalidate right behind the top-level arrival atomic (its XCC is idle by then) instead of after the top-level release
# speedup vs baseline: 1.0017x; 1.0017x over previous
; __device__ __forceinline__ int lane_id_() { int l; asm volatile("v_mbcnt_lo_u32_b32 %0, -1, 0\n\tv_mbcnt_hi_u32_b32 %0, -1, %0" : "=v"(l)); return l; }
; __device__ __forceinline__ unsigned xb_add(unsigned* p, unsigned v) { return __hip_atomic_fetch_add(p, v, __ATOMIC_RELAXED, __HIP_MEMORY_SCOPE_AGENT); }
; __device__ __forceinline__ void xcd_barrier(const XcdBarrier& b, const int WID) {
;     ...
;     if (WID == 0 && lane_id_() == 0) {
;         unsigned* bar = b.bar;
;         __builtin_amdgcn_s_waitcnt(0);
;         unsigned nloc = b.st[0], nx = b.st[1];
;         if (nloc == 0u) { xcd_barrier_complete(bar, b.x, nloc, nx); b.st[0] = nloc; b.st[1] = nx; }
;         const unsigned old = xb_add(&bar[XB_XSUB(b.x)], 1u);
;         const unsigned gen = old / nloc;
;         if (old + 1u == (gen + 1u) * nloc) {
;             __builtin_amdgcn_fence(__ATOMIC_RELEASE, "agent");
;             asm volatile("s_waitcnt vmcnt(0)" ::: "memory");
;             const unsigned og = xb_add(&bar[XB_TOP], 1u);
;             const unsigned tg = og / nx;
;             if (og + 1u == (tg + 1u) * nx) xb_add(&bar[XB_TOPGEN], 1u);
.Lgb_census_done:
	s_max_u32 s7, s7, 1
	s_max_u32 s8, s8, 1
	s_mov_b64 exec, 1
	v_mov_b32_e32 v2, 0x253f0
	v_mov_b32_e32 v3, s7
	ds_write_b32 v2, v3
	v_mov_b32_e32 v3, s8
	ds_write_b32 v2, v3 offset:4
	s_lshl_b32 s6, s3, 8
	s_add_u32 s9, s6, 0x1400
	v_mov_b32_e32 v2, s9
	v_mov_b32_e32 v3, 1
	global_atomic_add v1, v2, v3, s[4:5] sc0
	s_waitcnt vmcnt(0)
	v_readfirstlane_b32 s10, v1
	s_add_u32 s10, s10, 1
	s_add_u32 s9, s6, 0x2400
	s_cmp_lg_u32 s10, s7
	s_cbranch_scc1 .Lgb_follower
	buffer_wbl2 sc1
	s_waitcnt vmcnt(0) lgkmcnt(0)
	v_mov_b32_e32 v2, 0x3400
	global_atomic_add v1, v2, v3, s[4:5] sc0
	buffer_inv sc1
	s_waitcnt vmcnt(0)
	v_readfirstlane_b32 s10, v1
	s_add_u32 s10, s10, 1
	v_mov_b32_e32 v2, 0x3500
	s_cmp_lg_u32 s10, s8
	s_cbranch_scc1 .Lgb_topwait
	global_atomic_add v2, v3, s[4:5]
	s_branch .Lgb_topdone

; __device__ __forceinline__ unsigned xb_add(unsigned* p, unsigned v) { return __hip_atomic_fetch_add(p, v, __ATOMIC_RELAXED, __HIP_MEMORY_SCOPE_AGENT); }
; __device__ __forceinline__ void xcd_barrier(const XcdBarrier& b, const int WID) {
;     ...
;             __builtin_amdgcn_fence(__ATOMIC_ACQUIRE, "agent");
;             xb_add(&bar[XB_XGEN(b.x)], 1u);
;             asm volatile("s_waitcnt vmcnt(0)" ::: "memory");
.Lgb_topdone:
	s_waitcnt vmcnt(0)
	v_mov_b32_e32 v2, s9
	s_nop 0
	global_atomic_add v2, v3, s[4:5]
	s_waitcnt vmcnt(0)
	s_branch .Lgb_done

; __device__ __forceinline__ unsigned xb_ld(unsigned* p)              { return __hip_atomic_load(p, __ATOMIC_RELAXED, __HIP_MEMORY_SCOPE_AGENT); }
; __device__ __forceinline__ unsigned xb_add(unsigned* p, unsigned v) { return __hip_atomic_fetch_add(p, v, __ATOMIC_RELAXED, __HIP_MEMORY_SCOPE_AGENT); }
; #define XB_SPIN(cond, bar) do { unsigned _sp = 0; while (cond) { __builtin_amdgcn_s_sleep(1); \
;     if ((++_sp & 255u) == 0u) { if (xb_ld(&(bar)[XB_TMO])) break; if (_sp > XB_SPIN_CAP) { atomicAdd(&(bar)[XB_TMO], 1u); break; } } } } while (0)
; __device__ __forceinline__ void xcd_barrier(const XcdBarrier& b, const int WID) {
;     ...
;             const unsigned og = xb_add(&bar[XB_TOP], 1u);
;             const unsigned tg = og / nx;
;             if (og + 1u == (tg + 1u) * nx) xb_add(&bar[XB_TOPGEN], 1u);
;             else XB_SPIN(xb_ld(&bar[XB_TOPGEN]) == tg, bar);
.LBB0_130:
	s_or_b64 exec, exec, s[10:11]
	buffer_inv sc1
	s_waitcnt vmcnt(0)
	v_readfirstlane_b32 s8, v2
	v_cvt_f32_u32_e32 v2, v0
	v_sub_u32_e32 v3, 0, v0
	v_add_u32_e32 v1, s8, v1
	v_readlane_b32 s8, v251, 33
	v_rcp_iflag_f32_e32 v2, v2
	v_readlane_b32 s9, v251, 34
	s_mov_b64 s[10:11], -1
	v_mul_f32_e32 v2, 0x4f7ffffe, v2
	v_cvt_u32_f32_e32 v2, v2
	v_mul_lo_u32 v3, v3, v2
	v_mul_hi_u32 v3, v2, v3
	v_add_u32_e32 v2, v2, v3
	v_mul_hi_u32 v2, v1, v2
	v_mul_lo_u32 v3, v2, v0
	v_sub_u32_e32 v3, v1, v3
	v_cmp_ge_u32_e32 vcc, v3, v0
	v_add_u32_e32 v4, 1, v2
	v_add_u32_e32 v1, 1, v1
	v_cndmask_b32_e32 v2, v2, v4, vcc
	v_sub_u32_e32 v4, v3, v0
	v_cndmask_b32_e32 v3, v3, v4, vcc
	v_cmp_ge_u32_e32 vcc, v3, v0
	v_add_u32_e32 v3, 1, v2
	s_nop 0
	v_cndmask_b32_e32 v2, v2, v3, vcc
	v_mul_lo_u32 v3, v0, v2
	v_add_u32_e32 v0, v3, v0
	v_cmp_ne_u32_e32 vcc, v1, v0
	v_mov_b64_e32 v[0:1], s[8:9]
	s_and_saveexec_b64 s[8:9], vcc
	s_cbranch_execz .LBB0_142
	v_readlane_b32 s10, v251, 33
	v_mov_b32_e32 v0, 0
	v_readlane_b32 s11, v251, 34
	s_mov_b64 s[12:13], 0
	s_nop 3
	global_load_dword v1, v0, s[10:11] sc1
	s_waitcnt vmcnt(0)
	v_cmp_eq_u32_e32 vcc, v1, v2
	s_and_saveexec_b64 s[10:11], vcc
	s_cbranch_execz .LBB0_141
	s_mov_b32 s22, 1
	s_branch .LBB0_134

; __device__ __forceinline__ unsigned xb_ld(unsigned* p)              { return __hip_atomic_load(p, __ATOMIC_RELAXED, __HIP_MEMORY_SCOPE_AGENT); }
; __device__ __forceinline__ unsigned xb_add(unsigned* p, unsigned v) { return __hip_atomic_fetch_add(p, v, __ATOMIC_RELAXED, __HIP_MEMORY_SCOPE_AGENT); }
; #define XB_SPIN(cond, bar) do { unsigned _sp = 0; while (cond) { __builtin_amdgcn_s_sleep(1); \
;     if ((++_sp & 255u) == 0u) { if (xb_ld(&(bar)[XB_TMO])) break; if (_sp > XB_SPIN_CAP) { atomicAdd(&(bar)[XB_TMO], 1u); break; } } } } while (0)
; __device__ __forceinline__ void xcd_barrier(const XcdBarrier& b, const int WID) {
;     ...
;             else XB_SPIN(xb_ld(&bar[XB_TOPGEN]) == tg, bar);
;             __builtin_amdgcn_fence(__ATOMIC_ACQUIRE, "agent");
;             xb_add(&bar[XB_XGEN(b.x)], 1u);
.LBB0_144:
	s_or_b64 exec, exec, s[8:9]
	s_mov_b64 s[8:9], exec
	v_mbcnt_lo_u32_b32 v0, s8, 0
	v_mbcnt_hi_u32_b32 v0, s9, v0
	v_cmp_eq_u32_e32 vcc, 0, v0
	s_waitcnt vmcnt(0)
	s_and_saveexec_b64 s[10:11], vcc
	s_cbranch_execz .LBB0_146
	s_bcnt1_i32_b64 s8, s[8:9]
	v_mov_b32_e32 v1, s8
	v_readlane_b32 s8, v251, 29
	v_mov_b32_e32 v0, 0
	v_readlane_b32 s9, v251, 30
	s_nop 4
	global_atomic_add v0, v1, s[8:9]

; __device__ __forceinline__ unsigned xb_ld(unsigned* p)              { return __hip_atomic_load(p, __ATOMIC_RELAXED, __HIP_MEMORY_SCOPE_AGENT); }
; __device__ __forceinline__ unsigned xb_add(unsigned* p, unsigned v) { return __hip_atomic_fetch_add(p, v, __ATOMIC_RELAXED, __HIP_MEMORY_SCOPE_AGENT); }
; #define XB_SPIN(cond, bar) do { unsigned _sp = 0; while (cond) { __builtin_amdgcn_s_sleep(1); \
;     if ((++_sp & 255u) == 0u) { if (xb_ld(&(bar)[XB_TMO])) break; if (_sp > XB_SPIN_CAP) { atomicAdd(&(bar)[XB_TMO], 1u); break; } } } } while (0)
; __device__ __forceinline__ void xcd_barrier(const XcdBarrier& b, const int WID) {
;     ...
;             const unsigned og = xb_add(&bar[XB_TOP], 1u);
;             const unsigned tg = og / nx;
;             if (og + 1u == (tg + 1u) * nx) xb_add(&bar[XB_TOPGEN], 1u);
;             else XB_SPIN(xb_ld(&bar[XB_TOPGEN]) == tg, bar);
.LBB0_193:
	s_or_b64 exec, exec, s[8:9]
	buffer_inv sc1
	s_waitcnt vmcnt(0)
	v_readfirstlane_b32 s4, v2
	v_cvt_f32_u32_e32 v2, v0
	v_sub_u32_e32 v3, 0, v0
	v_add_u32_e32 v1, s4, v1
	v_readlane_b32 s4, v251, 33
	v_rcp_iflag_f32_e32 v2, v2
	v_readlane_b32 s5, v251, 34
	s_mov_b64 s[8:9], -1
	v_mul_f32_e32 v2, 0x4f7ffffe, v2
	v_cvt_u32_f32_e32 v2, v2
	v_mul_lo_u32 v3, v3, v2
	v_mul_hi_u32 v3, v2, v3
	v_add_u32_e32 v2, v2, v3
	v_mul_hi_u32 v2, v1, v2
	v_mul_lo_u32 v3, v2, v0
	v_sub_u32_e32 v3, v1, v3
	v_cmp_ge_u32_e32 vcc, v3, v0
	v_add_u32_e32 v4, 1, v2
	v_add_u32_e32 v1, 1, v1
	v_cndmask_b32_e32 v2, v2, v4, vcc
	v_sub_u32_e32 v4, v3, v0
	v_cndmask_b32_e32 v3, v3, v4, vcc
	v_cmp_ge_u32_e32 vcc, v3, v0
	v_add_u32_e32 v3, 1, v2
	s_nop 0
	v_cndmask_b32_e32 v2, v2, v3, vcc
	v_mul_lo_u32 v3, v0, v2
	v_add_u32_e32 v0, v3, v0
	v_cmp_ne_u32_e32 vcc, v1, v0
	v_mov_b64_e32 v[0:1], s[4:5]
	s_and_saveexec_b64 s[4:5], vcc
	s_cbranch_execz .LBB0_205
	v_readlane_b32 s8, v251, 33
	v_mov_b32_e32 v0, 0
	v_readlane_b32 s9, v251, 34
	s_mov_b64 s[10:11], 0
	s_nop 3
	global_load_dword v1, v0, s[8:9] sc1
	s_waitcnt vmcnt(0)
	v_cmp_eq_u32_e32 vcc, v1, v2
	s_and_saveexec_b64 s[8:9], vcc
	s_cbranch_execz .LBB0_204
	s_mov_b32 s17, 1
	s_branch .LBB0_197

; __device__ __forceinline__ unsigned xb_ld(unsigned* p)              { return __hip_atomic_load(p, __ATOMIC_RELAXED, __HIP_MEMORY_SCOPE_AGENT); }
; __device__ __forceinline__ unsigned xb_add(unsigned* p, unsigned v) { return __hip_atomic_fetch_add(p, v, __ATOMIC_RELAXED, __HIP_MEMORY_SCOPE_AGENT); }
; #define XB_SPIN(cond, bar) do { unsigned _sp = 0; while (cond) { __builtin_amdgcn_s_sleep(1); \
;     if ((++_sp & 255u) == 0u) { if (xb_ld(&(bar)[XB_TMO])) break; if (_sp > XB_SPIN_CAP) { atomicAdd(&(bar)[XB_TMO], 1u); break; } } } } while (0)
; __device__ __forceinline__ void xcd_barrier(const XcdBarrier& b, const int WID) {
;     ...
;             else XB_SPIN(xb_ld(&bar[XB_TOPGEN]) == tg, bar);
;             __builtin_amdgcn_fence(__ATOMIC_ACQUIRE, "agent");
;             xb_add(&bar[XB_XGEN(b.x)], 1u);
.LBB0_207:
	s_or_b64 exec, exec, s[4:5]
	s_mov_b64 s[4:5], exec
	v_mbcnt_lo_u32_b32 v0, s4, 0
	v_mbcnt_hi_u32_b32 v0, s5, v0
	v_cmp_eq_u32_e32 vcc, 0, v0
	s_waitcnt vmcnt(0)
	s_and_saveexec_b64 s[8:9], vcc
	s_cbranch_execz .LBB0_209
	s_bcnt1_i32_b64 s4, s[4:5]
	v_mov_b32_e32 v1, s4
	v_readlane_b32 s4, v251, 29
	v_mov_b32_e32 v0, 0
	v_readlane_b32 s5, v251, 30
	s_nop 4
	global_atomic_add v0, v1, s[4:5]

; __device__ __forceinline__ unsigned xb_ld(unsigned* p)              { return __hip_atomic_load(p, __ATOMIC_RELAXED, __HIP_MEMORY_SCOPE_AGENT); }
; __device__ __forceinline__ unsigned xb_add(unsigned* p, unsigned v) { return __hip_atomic_fetch_add(p, v, __ATOMIC_RELAXED, __HIP_MEMORY_SCOPE_AGENT); }
; #define XB_SPIN(cond, bar) do { unsigned _sp = 0; while (cond) { __builtin_amdgcn_s_sleep(1); \
;     if ((++_sp & 255u) == 0u) { if (xb_ld(&(bar)[XB_TMO])) break; if (_sp > XB_SPIN_CAP) { atomicAdd(&(bar)[XB_TMO], 1u); break; } } } } while (0)
; __device__ __forceinline__ void xcd_barrier(const XcdBarrier& b, const int WID) {
;     ...
;             const unsigned og = xb_add(&bar[XB_TOP], 1u);
;             const unsigned tg = og / nx;
;             if (og + 1u == (tg + 1u) * nx) xb_add(&bar[XB_TOPGEN], 1u);
;             else XB_SPIN(xb_ld(&bar[XB_TOPGEN]) == tg, bar);
.LBB0_638:
	s_or_b64 exec, exec, s[4:5]
	buffer_inv sc1
	s_waitcnt vmcnt(0)
	v_readfirstlane_b32 s2, v2
	v_cvt_f32_u32_e32 v2, v0
	v_sub_u32_e32 v3, 0, v0
	v_add_u32_e32 v1, s2, v1
	v_readlane_b32 s2, v251, 33
	v_rcp_iflag_f32_e32 v2, v2
	v_readlane_b32 s3, v251, 34
	s_mov_b64 s[4:5], -1
	v_mul_f32_e32 v2, 0x4f7ffffe, v2
	v_cvt_u32_f32_e32 v2, v2
	v_mul_lo_u32 v3, v3, v2
	v_mul_hi_u32 v3, v2, v3
	v_add_u32_e32 v2, v2, v3
	v_mul_hi_u32 v2, v1, v2
	v_mul_lo_u32 v3, v2, v0
	v_sub_u32_e32 v3, v1, v3
	v_cmp_ge_u32_e32 vcc, v3, v0
	v_add_u32_e32 v4, 1, v2
	v_add_u32_e32 v1, 1, v1
	v_cndmask_b32_e32 v2, v2, v4, vcc
	v_sub_u32_e32 v4, v3, v0
	v_cndmask_b32_e32 v3, v3, v4, vcc
	v_cmp_ge_u32_e32 vcc, v3, v0
	v_add_u32_e32 v3, 1, v2
	s_nop 0
	v_cndmask_b32_e32 v2, v2, v3, vcc
	v_mul_lo_u32 v3, v0, v2
	v_add_u32_e32 v0, v3, v0
	v_cmp_ne_u32_e32 vcc, v1, v0
	v_mov_b64_e32 v[0:1], s[2:3]
	s_and_saveexec_b64 s[2:3], vcc
	s_cbranch_execz .LBB0_650
	v_readlane_b32 s4, v251, 33
	v_mov_b32_e32 v0, 0
	v_readlane_b32 s5, v251, 34
	s_mov_b64 s[8:9], 0
	s_nop 3
	global_load_dword v1, v0, s[4:5] sc1
	s_waitcnt vmcnt(0)
	v_cmp_eq_u32_e32 vcc, v1, v2
	s_and_saveexec_b64 s[4:5], vcc
	s_cbranch_execz .LBB0_649
	s_mov_b32 s18, 1
	s_branch .LBB0_642

; __device__ __forceinline__ unsigned xb_ld(unsigned* p)              { return __hip_atomic_load(p, __ATOMIC_RELAXED, __HIP_MEMORY_SCOPE_AGENT); }
; __device__ __forceinline__ unsigned xb_add(unsigned* p, unsigned v) { return __hip_atomic_fetch_add(p, v, __ATOMIC_RELAXED, __HIP_MEMORY_SCOPE_AGENT); }
; #define XB_SPIN(cond, bar) do { unsigned _sp = 0; while (cond) { __builtin_amdgcn_s_sleep(1); \
;     if ((++_sp & 255u) == 0u) { if (xb_ld(&(bar)[XB_TMO])) break; if (_sp > XB_SPIN_CAP) { atomicAdd(&(bar)[XB_TMO], 1u); break; } } } } while (0)
; __device__ __forceinline__ void xcd_barrier(const XcdBarrier& b, const int WID) {
;     ...
;             else XB_SPIN(xb_ld(&bar[XB_TOPGEN]) == tg, bar);
;             __builtin_amdgcn_fence(__ATOMIC_ACQUIRE, "agent");
;             xb_add(&bar[XB_XGEN(b.x)], 1u);
.LBB0_652:
	s_or_b64 exec, exec, s[2:3]
	s_mov_b64 s[2:3], exec
	v_mbcnt_lo_u32_b32 v0, s2, 0
	v_mbcnt_hi_u32_b32 v0, s3, v0
	v_cmp_eq_u32_e32 vcc, 0, v0
	s_waitcnt vmcnt(0)
	s_and_saveexec_b64 s[4:5], vcc
	s_cbranch_execz .LBB0_654
	s_bcnt1_i32_b64 s2, s[2:3]
	v_mov_b32_e32 v1, s2
	v_readlane_b32 s2, v251, 29
	v_mov_b32_e32 v0, 0
	v_readlane_b32 s3, v251, 30
	s_nop 4
	global_atomic_add v0, v1, s[2:3]

; __device__ __forceinline__ unsigned xb_ld(unsigned* p)              { return __hip_atomic_load(p, __ATOMIC_RELAXED, __HIP_MEMORY_SCOPE_AGENT); }
; __device__ __forceinline__ unsigned xb_add(unsigned* p, unsigned v) { return __hip_atomic_fetch_add(p, v, __ATOMIC_RELAXED, __HIP_MEMORY_SCOPE_AGENT); }
; #define XB_SPIN(cond, bar) do { unsigned _sp = 0; while (cond) { __builtin_amdgcn_s_sleep(1); \
;     if ((++_sp & 255u) == 0u) { if (xb_ld(&(bar)[XB_TMO])) break; if (_sp > XB_SPIN_CAP) { atomicAdd(&(bar)[XB_TMO], 1u); break; } } } } while (0)
; __device__ __forceinline__ void xcd_barrier(const XcdBarrier& b, const int WID) {
;     ...
;             const unsigned og = xb_add(&bar[XB_TOP], 1u);
;             const unsigned tg = og / nx;
;             if (og + 1u == (tg + 1u) * nx) xb_add(&bar[XB_TOPGEN], 1u);
;             else XB_SPIN(xb_ld(&bar[XB_TOPGEN]) == tg, bar);
.LBB0_747:
	s_or_b64 exec, exec, s[8:9]
	buffer_inv sc1
	s_waitcnt vmcnt(0)
	v_readfirstlane_b32 s2, v2
	v_cvt_f32_u32_e32 v2, v0
	v_sub_u32_e32 v3, 0, v0
	v_add_u32_e32 v1, s2, v1
	v_readlane_b32 s2, v251, 33
	v_rcp_iflag_f32_e32 v2, v2
	v_readlane_b32 s3, v251, 34
	s_mov_b64 s[8:9], -1
	v_mul_f32_e32 v2, 0x4f7ffffe, v2
	v_cvt_u32_f32_e32 v2, v2
	v_mul_lo_u32 v3, v3, v2
	v_mul_hi_u32 v3, v2, v3
	v_add_u32_e32 v2, v2, v3
	v_mul_hi_u32 v2, v1, v2
	v_mul_lo_u32 v3, v2, v0
	v_sub_u32_e32 v3, v1, v3
	v_cmp_ge_u32_e32 vcc, v3, v0
	v_add_u32_e32 v4, 1, v2
	v_add_u32_e32 v1, 1, v1
	v_cndmask_b32_e32 v2, v2, v4, vcc
	v_sub_u32_e32 v4, v3, v0
	v_cndmask_b32_e32 v3, v3, v4, vcc
	v_cmp_ge_u32_e32 vcc, v3, v0
	v_add_u32_e32 v3, 1, v2
	s_nop 0
	v_cndmask_b32_e32 v2, v2, v3, vcc
	v_mul_lo_u32 v3, v0, v2
	v_add_u32_e32 v0, v3, v0
	v_cmp_ne_u32_e32 vcc, v1, v0
	v_mov_b64_e32 v[0:1], s[2:3]
	s_and_saveexec_b64 s[2:3], vcc
	s_cbranch_execz .LBB0_759
	v_readlane_b32 s8, v251, 33
	v_mov_b32_e32 v0, 0
	v_readlane_b32 s9, v251, 34
	s_mov_b64 s[10:11], 0
	s_nop 3
	global_load_dword v1, v0, s[8:9] sc1
	s_waitcnt vmcnt(0)
	v_cmp_eq_u32_e32 vcc, v1, v2
	s_and_saveexec_b64 s[8:9], vcc
	s_cbranch_execz .LBB0_758
	s_mov_b32 s25, 1
	s_branch .LBB0_751

; __device__ __forceinline__ unsigned xb_ld(unsigned* p)              { return __hip_atomic_load(p, __ATOMIC_RELAXED, __HIP_MEMORY_SCOPE_AGENT); }
; __device__ __forceinline__ unsigned xb_add(unsigned* p, unsigned v) { return __hip_atomic_fetch_add(p, v, __ATOMIC_RELAXED, __HIP_MEMORY_SCOPE_AGENT); }
; #define XB_SPIN(cond, bar) do { unsigned _sp = 0; while (cond) { __builtin_amdgcn_s_sleep(1); \
;     if ((++_sp & 255u) == 0u) { if (xb_ld(&(bar)[XB_TMO])) break; if (_sp > XB_SPIN_CAP) { atomicAdd(&(bar)[XB_TMO], 1u); break; } } } } while (0)
; __device__ __forceinline__ void xcd_barrier(const XcdBarrier& b, const int WID) {
;     ...
;             else XB_SPIN(xb_ld(&bar[XB_TOPGEN]) == tg, bar);
;             __builtin_amdgcn_fence(__ATOMIC_ACQUIRE, "agent");
;             xb_add(&bar[XB_XGEN(b.x)], 1u);
.LBB0_761:
	s_or_b64 exec, exec, s[2:3]
	s_mov_b64 s[2:3], exec
	v_mbcnt_lo_u32_b32 v0, s2, 0
	v_mbcnt_hi_u32_b32 v0, s3, v0
	v_cmp_eq_u32_e32 vcc, 0, v0
	s_waitcnt vmcnt(0)
	s_and_saveexec_b64 s[8:9], vcc
	s_cbranch_execz .LBB0_763
	s_bcnt1_i32_b64 s2, s[2:3]
	v_mov_b32_e32 v1, s2
	v_readlane_b32 s2, v251, 29
	v_mov_b32_e32 v0, 0
	v_readlane_b32 s3, v251, 30
	s_nop 4
	global_atomic_add v0, v1, s[2:3]

; __device__ __forceinline__ unsigned xb_ld(unsigned* p)              { return __hip_atomic_load(p, __ATOMIC_RELAXED, __HIP_MEMORY_SCOPE_AGENT); }
; __device__ __forceinline__ unsigned xb_add(unsigned* p, unsigned v) { return __hip_atomic_fetch_add(p, v, __ATOMIC_RELAXED, __HIP_MEMORY_SCOPE_AGENT); }
; #define XB_SPIN(cond, bar) do { unsigned _sp = 0; while (cond) { __builtin_amdgcn_s_sleep(1); \
;     if ((++_sp & 255u) == 0u) { if (xb_ld(&(bar)[XB_TMO])) break; if (_sp > XB_SPIN_CAP) { atomicAdd(&(bar)[XB_TMO], 1u); break; } } } } while (0)
; __device__ __forceinline__ void xcd_barrier(const XcdBarrier& b, const int WID) {
;     ...
;             const unsigned og = xb_add(&bar[XB_TOP], 1u);
;             const unsigned tg = og / nx;
;             if (og + 1u == (tg + 1u) * nx) xb_add(&bar[XB_TOPGEN], 1u);
;             else XB_SPIN(xb_ld(&bar[XB_TOPGEN]) == tg, bar);
.LBB0_851:
	s_or_b64 exec, exec, s[10:11]
	buffer_inv sc1
	s_waitcnt vmcnt(0)
	v_readfirstlane_b32 s8, v2
	v_cvt_f32_u32_e32 v2, v0
	v_sub_u32_e32 v3, 0, v0
	v_add_u32_e32 v1, s8, v1
	v_readlane_b32 s8, v251, 33
	v_rcp_iflag_f32_e32 v2, v2
	v_readlane_b32 s9, v251, 34
	s_mov_b64 s[10:11], -1
	v_mul_f32_e32 v2, 0x4f7ffffe, v2
	v_cvt_u32_f32_e32 v2, v2
	v_mul_lo_u32 v3, v3, v2
	v_mul_hi_u32 v3, v2, v3
	v_add_u32_e32 v2, v2, v3
	v_mul_hi_u32 v2, v1, v2
	v_mul_lo_u32 v3, v2, v0
	v_sub_u32_e32 v3, v1, v3
	v_cmp_ge_u32_e32 vcc, v3, v0
	v_add_u32_e32 v4, 1, v2
	v_add_u32_e32 v1, 1, v1
	v_cndmask_b32_e32 v2, v2, v4, vcc
	v_sub_u32_e32 v4, v3, v0
	v_cndmask_b32_e32 v3, v3, v4, vcc
	v_cmp_ge_u32_e32 vcc, v3, v0
	v_add_u32_e32 v3, 1, v2
	s_nop 0
	v_cndmask_b32_e32 v2, v2, v3, vcc
	v_mul_lo_u32 v3, v0, v2
	v_add_u32_e32 v0, v3, v0
	v_cmp_ne_u32_e32 vcc, v1, v0
	v_mov_b64_e32 v[0:1], s[8:9]
	s_and_saveexec_b64 s[8:9], vcc
	s_cbranch_execz .LBB0_863
	v_readlane_b32 s10, v251, 33
	v_mov_b32_e32 v0, 0
	v_readlane_b32 s11, v251, 34
	s_mov_b64 s[12:13], 0
	s_nop 3
	global_load_dword v1, v0, s[10:11] sc1
	s_waitcnt vmcnt(0)
	v_cmp_eq_u32_e32 vcc, v1, v2
	s_and_saveexec_b64 s[10:11], vcc
	s_cbranch_execz .LBB0_862
	s_mov_b32 s25, 1
	s_branch .LBB0_855

; __device__ __forceinline__ unsigned xb_ld(unsigned* p)              { return __hip_atomic_load(p, __ATOMIC_RELAXED, __HIP_MEMORY_SCOPE_AGENT); }
; __device__ __forceinline__ unsigned xb_add(unsigned* p, unsigned v) { return __hip_atomic_fetch_add(p, v, __ATOMIC_RELAXED, __HIP_MEMORY_SCOPE_AGENT); }
; #define XB_SPIN(cond, bar) do { unsigned _sp = 0; while (cond) { __builtin_amdgcn_s_sleep(1); \
;     if ((++_sp & 255u) == 0u) { if (xb_ld(&(bar)[XB_TMO])) break; if (_sp > XB_SPIN_CAP) { atomicAdd(&(bar)[XB_TMO], 1u); break; } } } } while (0)
; __device__ __forceinline__ void xcd_barrier(const XcdBarrier& b, const int WID) {
;     ...
;             const unsigned og = xb_add(&bar[XB_TOP], 1u);
;             const unsigned tg = og / nx;
;             if (og + 1u == (tg + 1u) * nx) xb_add(&bar[XB_TOPGEN], 1u);
;             else XB_SPIN(xb_ld(&bar[XB_TOPGEN]) == tg, bar);
.LBB0_970:
	s_or_b64 exec, exec, s[10:11]
	buffer_inv sc1
	s_waitcnt vmcnt(0)
	v_readfirstlane_b32 s8, v2
	v_cvt_f32_u32_e32 v2, v0
	v_sub_u32_e32 v3, 0, v0
	v_add_u32_e32 v1, s8, v1
	s_mov_b64 s[10:11], -1
	v_rcp_iflag_f32_e32 v2, v2
	s_nop 0
	v_mul_f32_e32 v2, 0x4f7ffffe, v2
	v_cvt_u32_f32_e32 v2, v2
	v_mul_lo_u32 v3, v3, v2
	v_mul_hi_u32 v3, v2, v3
	v_add_u32_e32 v2, v2, v3
	v_mul_hi_u32 v2, v1, v2
	v_mul_lo_u32 v3, v2, v0
	v_sub_u32_e32 v3, v1, v3
	v_cmp_ge_u32_e32 vcc, v3, v0
	v_add_u32_e32 v4, 1, v2
	v_add_u32_e32 v1, 1, v1
	v_cndmask_b32_e32 v2, v2, v4, vcc
	v_sub_u32_e32 v4, v3, v0
	v_cndmask_b32_e32 v3, v3, v4, vcc
	v_cmp_ge_u32_e32 vcc, v3, v0
	v_add_u32_e32 v3, 1, v2
	s_nop 0
	v_cndmask_b32_e32 v2, v2, v3, vcc
	v_mul_lo_u32 v3, v0, v2
	v_add_u32_e32 v0, v3, v0
	v_cmp_ne_u32_e32 vcc, v1, v0
	v_mov_b64_e32 v[0:1], s[58:59]
	s_and_saveexec_b64 s[8:9], vcc
	s_cbranch_execz .LBB0_982
	v_mov_b32_e32 v0, 0
	global_load_dword v1, v0, s[58:59] sc1
	s_mov_b64 s[12:13], 0
	s_waitcnt vmcnt(0)
	v_cmp_eq_u32_e32 vcc, v1, v2
	s_and_saveexec_b64 s[10:11], vcc
	s_cbranch_execz .LBB0_981
	s_mov_b32 s25, 1
	s_branch .LBB0_974

; __device__ __forceinline__ unsigned xb_ld(unsigned* p)              { return __hip_atomic_load(p, __ATOMIC_RELAXED, __HIP_MEMORY_SCOPE_AGENT); }
; __device__ __forceinline__ unsigned xb_add(unsigned* p, unsigned v) { return __hip_atomic_fetch_add(p, v, __ATOMIC_RELAXED, __HIP_MEMORY_SCOPE_AGENT); }
; #define XB_SPIN(cond, bar) do { unsigned _sp = 0; while (cond) { __builtin_amdgcn_s_sleep(1); \
;     if ((++_sp & 255u) == 0u) { if (xb_ld(&(bar)[XB_TMO])) break; if (_sp > XB_SPIN_CAP) { atomicAdd(&(bar)[XB_TMO], 1u); break; } } } } while (0)
; __device__ __forceinline__ void xcd_barrier(const XcdBarrier& b, const int WID) {
;     ...
;             const unsigned og = xb_add(&bar[XB_TOP], 1u);
;             const unsigned tg = og / nx;
;             if (og + 1u == (tg + 1u) * nx) xb_add(&bar[XB_TOPGEN], 1u);
;             else XB_SPIN(xb_ld(&bar[XB_TOPGEN]) == tg, bar);
.LBB0_1062:
	s_or_b64 exec, exec, s[4:5]
	buffer_inv sc1
	v_cvt_f32_u32_e32 v3, v0
	s_waitcnt vmcnt(0)
	v_readfirstlane_b32 s2, v2
	s_mov_b64 s[4:5], -1
	v_rcp_iflag_f32_e32 v3, v3
	v_add_u32_e32 v1, s2, v1
	v_add_u32_e32 v4, 1, v1
	v_mul_f32_e32 v2, 0x4f7ffffe, v3
	v_cvt_u32_f32_e32 v2, v2
	v_sub_u32_e32 v3, 0, v0
	v_mul_lo_u32 v3, v3, v2
	v_mul_hi_u32 v3, v2, v3
	v_add_u32_e32 v2, v2, v3
	v_mul_hi_u32 v2, v1, v2
	v_mul_lo_u32 v3, v2, v0
	v_sub_u32_e32 v1, v1, v3
	v_add_u32_e32 v5, 1, v2
	v_cmp_ge_u32_e32 vcc, v1, v0
	v_sub_u32_e32 v3, v1, v0
	s_nop 0
	v_cndmask_b32_e32 v2, v2, v5, vcc
	v_cndmask_b32_e32 v1, v1, v3, vcc
	v_add_u32_e32 v3, 1, v2
	v_cmp_ge_u32_e32 vcc, v1, v0
	s_nop 1
	v_cndmask_b32_e32 v2, v2, v3, vcc
	v_mul_lo_u32 v1, v0, v2
	v_add_u32_e32 v0, v1, v0
	v_cmp_ne_u32_e32 vcc, v4, v0
	v_mov_b64_e32 v[0:1], s[58:59]
	s_and_saveexec_b64 s[2:3], vcc
	s_cbranch_execz .LBB0_1074
	v_mov_b32_e32 v0, 0
	global_load_dword v1, v0, s[58:59] sc1
	s_mov_b64 s[6:7], 0
	s_waitcnt vmcnt(0)
	v_cmp_eq_u32_e32 vcc, v1, v2
	s_and_saveexec_b64 s[4:5], vcc
	s_cbranch_execz .LBB0_1073
	s_mov_b32 s16, 1
	s_branch .LBB0_1066
